# wave-sum butterflies via DPP+permlane swaps instead of ds_bpermute; attention next-tile LDS writes issued before PV
# speedup vs baseline: 1.0176x; 1.0025x over previous
.LBB0_84:
	v_ashrrev_i32_e32 v17, 31, v16
	v_lshlrev_b64 v[18:19], 12, v[16:17]
	v_lshl_add_u64 v[58:59], v[32:33], 0, v[18:19]
	global_load_dwordx4 v[42:45], v[58:59], off offset:1024
	global_load_dwordx4 v[46:49], v[58:59], off
	global_load_dwordx4 v[50:53], v[58:59], off offset:3072
	global_load_dwordx4 v[54:57], v[58:59], off offset:2048
	v_add_u32_e32 v34, s9, v16
	v_cmp_gt_i32_e32 vcc, s73, v34
	s_waitcnt vmcnt(3)
	v_mov_b32_e32 v62, v43
	v_cndmask_b32_e32 v16, v16, v34, vcc
	v_ashrrev_i32_e32 v17, 31, v16
	v_lshlrev_b64 v[16:17], 12, v[16:17]
	v_lshl_add_u64 v[16:17], v[32:33], 0, v[16:17]
	global_load_dwordx4 v[28:31], v[16:17], off
	global_load_dwordx4 v[24:27], v[16:17], off offset:1024
	global_load_dwordx4 v[20:23], v[16:17], off offset:2048
	s_nop 0
	global_load_dwordx4 v[16:19], v[16:17], off offset:3072
	s_waitcnt vmcnt(6)
	v_mov_b32_e32 v63, v47
	v_mov_b32_e32 v60, v42
	v_mov_b32_e32 v61, v46
	s_waitcnt vmcnt(5)
	v_mov_b32_e32 v70, v51
	s_waitcnt vmcnt(4)
	v_mov_b32_e32 v71, v55
	v_pk_mul_f32 v[62:63], v[62:63], v[62:63]
	v_mov_b32_e32 v64, v44
	v_mov_b32_e32 v65, v48
	v_mov_b32_e32 v68, v50
	v_mov_b32_e32 v69, v54
	v_pk_mul_f32 v[70:71], v[70:71], v[70:71]
	v_pk_fma_f32 v[60:61], v[60:61], v[60:61], v[62:63]
	v_mov_b32_e32 v66, v45
	v_mov_b32_e32 v67, v49
	v_mov_b32_e32 v72, v52
	v_mov_b32_e32 v73, v56
	v_pk_fma_f32 v[62:63], v[68:69], v[68:69], v[70:71]
	v_pk_fma_f32 v[60:61], v[64:65], v[64:65], v[60:61]
	v_mov_b32_e32 v74, v53
	v_mov_b32_e32 v75, v57
	v_pk_fma_f32 v[62:63], v[72:73], v[72:73], v[62:63]
	v_pk_fma_f32 v[60:61], v[66:67], v[66:67], v[60:61]
	v_pk_fma_f32 v[62:63], v[74:75], v[74:75], v[62:63]
	v_add_f32_e32 v35, v60, v61
	v_add_f32_e32 v35, v63, v35
	v_add_f32_e32 v35, v62, v35
	s_waitcnt lgkmcnt(0)
	s_nop 1
	v_add_f32_dpp v35, v35, v35 quad_perm:[1,0,3,2] row_mask:0xf bank_mask:0xf
	s_waitcnt lgkmcnt(0)
	s_nop 1
	v_add_f32_dpp v35, v35, v35 quad_perm:[2,3,0,1] row_mask:0xf bank_mask:0xf
	s_waitcnt lgkmcnt(0)
	s_nop 1
	v_add_f32_dpp v35, v35, v35 row_half_mirror row_mask:0xf bank_mask:0xf
	s_waitcnt lgkmcnt(0)
	s_nop 1
	v_add_f32_dpp v35, v35, v35 row_mirror row_mask:0xf bank_mask:0xf
	s_waitcnt lgkmcnt(0)
	v_mov_b32_e32 v60, v35
	s_nop 1
	v_permlane16_swap_b32_e32 v35, v60
	v_add_f32_e32 v35, v35, v60
	s_waitcnt lgkmcnt(0)
	v_mov_b32_e32 v60, v35
	s_nop 1
	v_permlane32_swap_b32_e32 v35, v60
	v_add_f32_e32 v35, v35, v60
	v_fmamk_f32 v35, v35, 0x3a800000, v158
	v_mul_f32_e32 v60, 0x4b800000, v35
	v_cmp_gt_f32_e64 s[38:39], s82, v35
	s_nop 1
	v_cndmask_b32_e64 v35, v35, v60, s[38:39]
	v_rsq_f32_e32 v35, v35
	s_nop 0
	v_mul_f32_e32 v60, 0x45800000, v35
	v_cndmask_b32_e64 v60, v35, v60, s[38:39]
	v_pk_mul_f32 v[46:47], v[46:47], v[60:61] op_sel_hi:[1,0]
	v_pk_mul_f32 v[48:49], v[48:49], v[60:61] op_sel_hi:[1,0]
	v_pk_mul_f32 v[62:63], v[42:43], v[60:61] op_sel_hi:[1,0]
	v_pk_mul_f32 v[64:65], v[44:45], v[60:61] op_sel_hi:[1,0]
	v_pk_mul_f32 v[54:55], v[54:55], v[60:61] op_sel_hi:[1,0]
	v_pk_mul_f32 v[56:57], v[56:57], v[60:61] op_sel_hi:[1,0]
	v_pk_mul_f32 v[66:67], v[50:51], v[60:61] op_sel_hi:[1,0]
	v_pk_mul_f32 v[60:61], v[52:53], v[60:61] op_sel_hi:[1,0]
	v_pk_mul_f32 v[44:45], v[2:3], v[48:49]
	v_pk_mul_f32 v[42:43], v[0:1], v[46:47]
	v_pk_mul_f32 v[48:49], v[6:7], v[64:65]
	v_pk_mul_f32 v[46:47], v[4:5], v[62:63]
	v_pk_mul_f32 v[52:53], v[10:11], v[56:57]
	v_pk_mul_f32 v[50:51], v[8:9], v[54:55]
	v_pk_mul_f32 v[56:57], v[14:15], v[60:61]
	v_pk_mul_f32 v[54:55], v[12:13], v[66:67]
	global_store_dwordx4 v[58:59], v[42:45], off
	global_store_dwordx4 v[58:59], v[46:49], off offset:1024
	global_store_dwordx4 v[58:59], v[50:53], off offset:2048
	global_store_dwordx4 v[58:59], v[54:57], off offset:3072
	s_and_saveexec_b64 s[2:3], vcc
	s_cbranch_execz .LBB0_83
	s_waitcnt vmcnt(7)
	v_mov_b32_e32 v44, v29
	s_waitcnt vmcnt(6)
	v_mov_b32_e32 v45, v25
	v_mov_b32_e32 v42, v28
	v_mov_b32_e32 v43, v24
	v_pk_mul_f32 v[44:45], v[44:45], v[44:45]
	s_waitcnt vmcnt(5)
	v_mov_b32_e32 v46, v21
	v_pk_fma_f32 v[42:43], v[42:43], v[42:43], v[44:45]
	v_mov_b32_e32 v44, v30
	v_mov_b32_e32 v45, v26
	v_pk_fma_f32 v[42:43], v[44:45], v[44:45], v[42:43]
	v_mov_b32_e32 v44, v31
	v_mov_b32_e32 v45, v27
	s_waitcnt vmcnt(4)
	v_mov_b32_e32 v47, v17
	v_pk_fma_f32 v[42:43], v[44:45], v[44:45], v[42:43]
	v_mov_b32_e32 v44, v20
	v_mov_b32_e32 v45, v16
	v_pk_mul_f32 v[46:47], v[46:47], v[46:47]
	v_add_f32_e32 v35, v42, v43
	v_pk_fma_f32 v[44:45], v[44:45], v[44:45], v[46:47]
	v_mov_b32_e32 v46, v22
	v_mov_b32_e32 v47, v18
	v_pk_fma_f32 v[44:45], v[46:47], v[46:47], v[44:45]
	v_mov_b32_e32 v46, v23
	v_mov_b32_e32 v47, v19
	v_pk_fma_f32 v[44:45], v[46:47], v[46:47], v[44:45]
	s_nop 0
	v_add_f32_e32 v35, v35, v44
	v_add_f32_e32 v35, v35, v45
	s_waitcnt lgkmcnt(0)
	s_nop 1
	v_add_f32_dpp v35, v35, v35 quad_perm:[1,0,3,2] row_mask:0xf bank_mask:0xf
	s_waitcnt lgkmcnt(0)
	s_nop 1
	v_add_f32_dpp v35, v35, v35 quad_perm:[2,3,0,1] row_mask:0xf bank_mask:0xf
	s_waitcnt lgkmcnt(0)
	s_nop 1
	v_add_f32_dpp v35, v35, v35 row_half_mirror row_mask:0xf bank_mask:0xf
	s_waitcnt lgkmcnt(0)
	s_nop 1
	v_add_f32_dpp v35, v35, v35 row_mirror row_mask:0xf bank_mask:0xf
	s_waitcnt lgkmcnt(0)
	v_mov_b32_e32 v42, v35
	s_nop 1
	v_permlane16_swap_b32_e32 v35, v42
	v_add_f32_e32 v35, v35, v42
	s_waitcnt lgkmcnt(0)
	v_mov_b32_e32 v42, v35
	s_nop 1
	v_permlane32_swap_b32_e32 v35, v42
	v_add_f32_e32 v35, v35, v42
	v_fmamk_f32 v35, v35, 0x3a800000, v158
	v_mul_f32_e32 v42, 0x4b800000, v35
	v_cmp_gt_f32_e32 vcc, s82, v35
	s_nop 1
	v_cndmask_b32_e32 v35, v35, v42, vcc
	v_rsq_f32_e32 v44, v35
	v_ashrrev_i32_e32 v35, 31, v34
	v_lshlrev_b64 v[42:43], 12, v[34:35]
	v_lshl_add_u64 v[42:43], v[32:33], 0, v[42:43]
	v_mul_f32_e32 v35, 0x45800000, v44
	v_cndmask_b32_e32 v44, v44, v35, vcc
	v_pk_mul_f32 v[28:29], v[28:29], v[44:45] op_sel_hi:[1,0]
	v_pk_mul_f32 v[30:31], v[30:31], v[44:45] op_sel_hi:[1,0]
	v_pk_mul_f32 v[46:47], v[24:25], v[44:45] op_sel_hi:[1,0]
	v_pk_mul_f32 v[48:49], v[26:27], v[44:45] op_sel_hi:[1,0]
	v_pk_mul_f32 v[26:27], v[2:3], v[30:31]
	v_pk_mul_f32 v[24:25], v[0:1], v[28:29]
	v_pk_mul_f32 v[20:21], v[20:21], v[44:45] op_sel_hi:[1,0]
	v_pk_mul_f32 v[22:23], v[22:23], v[44:45] op_sel_hi:[1,0]
	v_pk_mul_f32 v[16:17], v[16:17], v[44:45] op_sel_hi:[1,0]
	v_pk_mul_f32 v[18:19], v[18:19], v[44:45] op_sel_hi:[1,0]
	global_store_dwordx4 v[42:43], v[24:27], off
	v_pk_mul_f32 v[22:23], v[10:11], v[22:23]
	v_pk_mul_f32 v[20:21], v[8:9], v[20:21]
	v_pk_mul_f32 v[26:27], v[6:7], v[48:49]
	v_pk_mul_f32 v[24:25], v[4:5], v[46:47]
	v_pk_mul_f32 v[18:19], v[14:15], v[18:19]
	v_pk_mul_f32 v[16:17], v[12:13], v[16:17]
	global_store_dwordx4 v[42:43], v[24:27], off offset:1024
	global_store_dwordx4 v[42:43], v[20:23], off offset:2048
	global_store_dwordx4 v[42:43], v[16:19], off offset:3072
	s_branch .LBB0_83

.LBB0_100:
	s_or_b64 exec, exec, s[2:3]
	v_mul_f32_e32 v36, v29, v29
	v_mul_f32_e32 v37, v25, v25
	v_fmac_f32_e32 v36, v28, v28
	v_fmac_f32_e32 v37, v24, v24
	v_fmac_f32_e32 v36, v30, v30
	v_fmac_f32_e32 v37, v26, v26
	v_fmac_f32_e32 v36, v31, v31
	v_fmac_f32_e32 v37, v27, v27
	v_add_f32_e32 v36, v36, v37
	v_mul_f32_e32 v37, v21, v21
	v_fmac_f32_e32 v37, v20, v20
	v_fmac_f32_e32 v37, v22, v22
	v_fmac_f32_e32 v37, v23, v23
	v_add_f32_e32 v36, v36, v37
	v_mul_f32_e32 v37, v17, v17
	v_fmac_f32_e32 v37, v16, v16
	v_fmac_f32_e32 v37, v18, v18
	v_fmac_f32_e32 v37, v19, v19
	v_add_f32_e32 v36, v36, v37
	v_ashrrev_i32_e32 v135, 31, v134
	v_pk_add_f32 v[44:45], v[50:51], 1.0 op_sel_hi:[1,0]
	v_pk_add_f32 v[46:47], v[48:49], 1.0 op_sel_hi:[1,0]
	v_lshlrev_b64 v[38:39], 11, v[134:135]
	s_waitcnt lgkmcnt(0)
	s_nop 1
	v_add_f32_dpp v36, v36, v36 quad_perm:[1,0,3,2] row_mask:0xf bank_mask:0xf
	s_waitcnt lgkmcnt(0)
	s_nop 1
	v_add_f32_dpp v36, v36, v36 quad_perm:[2,3,0,1] row_mask:0xf bank_mask:0xf
	s_waitcnt lgkmcnt(0)
	s_nop 1
	v_add_f32_dpp v36, v36, v36 row_half_mirror row_mask:0xf bank_mask:0xf
	s_waitcnt lgkmcnt(0)
	s_nop 1
	v_add_f32_dpp v36, v36, v36 row_mirror row_mask:0xf bank_mask:0xf
	s_waitcnt lgkmcnt(0)
	v_mov_b32_e32 v37, v36
	s_nop 1
	v_permlane16_swap_b32_e32 v36, v37
	v_add_f32_e32 v36, v36, v37
	s_waitcnt lgkmcnt(0)
	v_mov_b32_e32 v37, v36
	s_nop 1
	v_permlane32_swap_b32_e32 v36, v37
	v_add_f32_e32 v36, v36, v37
	v_fmamk_f32 v36, v36, 0x3a800000, v158
	v_cmp_gt_f32_e32 vcc, s82, v36
	v_mul_f32_e32 v37, 0x4b800000, v36
	s_nop 0
	v_cndmask_b32_e32 v36, v36, v37, vcc
	v_rsq_f32_e32 v36, v36
	s_nop 0
	v_mul_f32_e32 v37, 0x45800000, v36
	v_cndmask_b32_e32 v36, v36, v37, vcc
	v_pk_mul_f32 v[30:31], v[30:31], v[36:37] op_sel_hi:[1,0]
	v_pk_mul_f32 v[28:29], v[28:29], v[36:37] op_sel_hi:[1,0]
	v_pk_mul_f32 v[30:31], v[2:3], v[30:31]
	v_pk_mul_f32 v[28:29], v[0:1], v[28:29]
	v_pk_fma_f32 v[30:31], v[44:45], v[30:31], v[54:55]
	v_pk_fma_f32 v[28:29], v[46:47], v[28:29], v[52:53]
	v_pk_mul_f32 v[24:25], v[24:25], v[36:37] op_sel_hi:[1,0]
	v_cvt_pk_bf16_f32 v28, v28, v29
	v_cvt_pk_bf16_f32 v29, v30, v31
	v_lshl_add_u64 v[30:31], v[128:129], 0, v[38:39]
	v_pk_mul_f32 v[26:27], v[26:27], v[36:37] op_sel_hi:[1,0]
	v_pk_mul_f32 v[24:25], v[4:5], v[24:25]
	v_pk_add_f32 v[38:39], v[40:41], 1.0 op_sel_hi:[1,0]
	global_store_dwordx2 v[30:31], v[28:29], off
	v_pk_mul_f32 v[26:27], v[6:7], v[26:27]
	v_pk_add_f32 v[28:29], v[42:43], 1.0 op_sel_hi:[1,0]
	v_pk_fma_f32 v[24:25], v[38:39], v[24:25], v[32:33]
	v_pk_fma_f32 v[26:27], v[28:29], v[26:27], v[34:35]
	v_cvt_pk_bf16_f32 v24, v24, v25
	v_pk_mul_f32 v[22:23], v[22:23], v[36:37] op_sel_hi:[1,0]
	v_cvt_pk_bf16_f32 v25, v26, v27
	v_pk_mul_f32 v[20:21], v[20:21], v[36:37] op_sel_hi:[1,0]
	global_store_dwordx2 v[30:31], v[24:25], off offset:512
	v_pk_mul_f32 v[20:21], v[8:9], v[20:21]
	v_pk_mul_f32 v[22:23], v[10:11], v[22:23]
	v_pk_add_f32 v[24:25], v[62:63], 1.0 op_sel_hi:[1,0]
	v_pk_add_f32 v[26:27], v[60:61], 1.0 op_sel_hi:[1,0]
	v_pk_fma_f32 v[22:23], v[24:25], v[22:23], v[58:59]
	v_pk_fma_f32 v[20:21], v[26:27], v[20:21], v[56:57]
	v_pk_mul_f32 v[16:17], v[16:17], v[36:37] op_sel_hi:[1,0]
	v_cvt_pk_bf16_f32 v20, v20, v21
	v_cvt_pk_bf16_f32 v21, v22, v23
	v_pk_mul_f32 v[18:19], v[18:19], v[36:37] op_sel_hi:[1,0]
	v_pk_mul_f32 v[16:17], v[12:13], v[16:17]
	s_waitcnt vmcnt(7)
	v_pk_add_f32 v[22:23], v[80:81], 1.0 op_sel_hi:[1,0]
	global_store_dwordx2 v[30:31], v[20:21], off offset:1024
	v_pk_mul_f32 v[18:19], v[14:15], v[18:19]
	v_pk_add_f32 v[20:21], v[82:83], 1.0 op_sel_hi:[1,0]
	s_waitcnt vmcnt(7)
	v_pk_fma_f32 v[16:17], v[22:23], v[16:17], v[76:77]
	v_pk_fma_f32 v[18:19], v[20:21], v[18:19], v[78:79]
	v_cvt_pk_bf16_f32 v16, v16, v17
	s_nop 0
	v_cvt_pk_bf16_f32 v17, v18, v19
	global_store_dwordx2 v[30:31], v[16:17], off offset:1536

.LBB0_128:
	s_or_b64 exec, exec, s[2:3]
	v_mul_f32_e32 v92, v117, v117
	v_mul_f32_e32 v93, v113, v113
	v_fmac_f32_e32 v92, v116, v116
	v_fmac_f32_e32 v93, v112, v112
	v_fmac_f32_e32 v92, v118, v118
	v_fmac_f32_e32 v93, v114, v114
	v_fmac_f32_e32 v92, v119, v119
	v_fmac_f32_e32 v93, v115, v115
	v_add_f32_e32 v92, v92, v93
	v_mul_f32_e32 v93, v89, v89
	v_fmac_f32_e32 v93, v88, v88
	v_fmac_f32_e32 v93, v90, v90
	v_fmac_f32_e32 v93, v91, v91
	v_add_f32_e32 v92, v92, v93
	v_mul_f32_e32 v93, v73, v73
	v_fmac_f32_e32 v93, v72, v72
	v_fmac_f32_e32 v93, v74, v74
	v_fmac_f32_e32 v93, v75, v75
	v_add_f32_e32 v92, v92, v93
	v_pk_add_f32 v[20:21], v[20:21], 1.0 op_sel_hi:[1,0]
	v_pk_add_f32 v[22:23], v[22:23], 1.0 op_sel_hi:[1,0]
	s_waitcnt lgkmcnt(0)
	s_nop 1
	v_add_f32_dpp v92, v92, v92 quad_perm:[1,0,3,2] row_mask:0xf bank_mask:0xf
	s_waitcnt lgkmcnt(0)
	s_nop 1
	v_add_f32_dpp v92, v92, v92 quad_perm:[2,3,0,1] row_mask:0xf bank_mask:0xf
	s_waitcnt lgkmcnt(0)
	s_nop 1
	v_add_f32_dpp v92, v92, v92 row_half_mirror row_mask:0xf bank_mask:0xf
	s_waitcnt lgkmcnt(0)
	s_nop 1
	v_add_f32_dpp v92, v92, v92 row_mirror row_mask:0xf bank_mask:0xf
	s_waitcnt lgkmcnt(0)
	v_mov_b32_e32 v93, v92
	s_nop 1
	v_permlane16_swap_b32_e32 v92, v93
	v_add_f32_e32 v92, v92, v93
	s_waitcnt lgkmcnt(0)
	v_mov_b32_e32 v93, v92
	s_nop 1
	v_permlane32_swap_b32_e32 v92, v93
	v_add_f32_e32 v92, v92, v93
	v_fmamk_f32 v92, v92, 0x3a800000, v158
	v_cmp_gt_f32_e32 vcc, s82, v92
	v_mul_f32_e32 v93, 0x4b800000, v92
	s_nop 0
	v_cndmask_b32_e32 v92, v92, v93, vcc
	v_rsq_f32_e32 v92, v92
	s_nop 0
	v_mul_f32_e32 v93, 0x45800000, v92
	v_cndmask_b32_e32 v92, v92, v93, vcc
	v_pk_mul_f32 v[100:101], v[116:117], v[92:93] op_sel_hi:[1,0]
	v_pk_mul_f32 v[94:95], v[118:119], v[92:93] op_sel_hi:[1,0]
	v_pk_mul_f32 v[100:101], v[0:1], v[100:101]
	v_pk_mul_f32 v[94:95], v[2:3], v[94:95]
	v_pk_fma_f32 v[20:21], v[20:21], v[100:101], v[24:25]
	v_pk_fma_f32 v[22:23], v[22:23], v[94:95], v[26:27]
	v_cvt_pk_bf16_f32 v20, v20, v21
	v_pk_add_f32 v[24:25], v[30:31], 1.0 op_sel_hi:[1,0]
	v_cvt_pk_bf16_f32 v21, v22, v23
	global_store_dwordx2 v[132:133], v[20:21], off offset:-1024
	v_pk_mul_f32 v[20:21], v[114:115], v[92:93] op_sel_hi:[1,0]
	v_pk_mul_f32 v[22:23], v[112:113], v[92:93] op_sel_hi:[1,0]
	v_pk_mul_f32 v[20:21], v[6:7], v[20:21]
	v_pk_mul_f32 v[22:23], v[4:5], v[22:23]
	v_pk_add_f32 v[26:27], v[28:29], 1.0 op_sel_hi:[1,0]
	v_pk_fma_f32 v[18:19], v[24:25], v[20:21], v[18:19]
	v_pk_fma_f32 v[16:17], v[26:27], v[22:23], v[16:17]
	v_pk_add_f32 v[22:23], v[44:45], 1.0 op_sel_hi:[1,0]
	v_cvt_pk_bf16_f32 v16, v16, v17
	v_cvt_pk_bf16_f32 v17, v18, v19
	v_pk_mul_f32 v[18:19], v[88:89], v[92:93] op_sel_hi:[1,0]
	global_store_dwordx2 v[132:133], v[16:17], off offset:-512
	v_pk_mul_f32 v[16:17], v[90:91], v[92:93] op_sel_hi:[1,0]
	v_pk_mul_f32 v[18:19], v[8:9], v[18:19]
	v_pk_mul_f32 v[16:17], v[10:11], v[16:17]
	v_pk_add_f32 v[20:21], v[46:47], 1.0 op_sel_hi:[1,0]
	v_pk_fma_f32 v[18:19], v[22:23], v[18:19], v[36:37]
	v_pk_fma_f32 v[16:17], v[20:21], v[16:17], v[38:39]
	v_cvt_pk_bf16_f32 v18, v18, v19
	s_waitcnt vmcnt(15)
	v_pk_add_f32 v[22:23], v[68:69], 1.0 op_sel_hi:[1,0]
	v_cvt_pk_bf16_f32 v19, v16, v17
	global_store_dwordx2 v[132:133], v[18:19], off
	v_pk_mul_f32 v[18:19], v[72:73], v[92:93] op_sel_hi:[1,0]
	v_pk_mul_f32 v[16:17], v[74:75], v[92:93] op_sel_hi:[1,0]
	v_pk_mul_f32 v[18:19], v[12:13], v[18:19]
	v_pk_mul_f32 v[16:17], v[14:15], v[16:17]
	v_pk_add_f32 v[20:21], v[70:71], 1.0 op_sel_hi:[1,0]
	s_waitcnt vmcnt(15)
	v_pk_fma_f32 v[18:19], v[22:23], v[18:19], v[64:65]
	v_pk_fma_f32 v[16:17], v[20:21], v[16:17], v[66:67]
	v_cvt_pk_bf16_f32 v18, v18, v19
	s_nop 0
	v_cvt_pk_bf16_f32 v19, v16, v17
	global_store_dwordx2 v[132:133], v[18:19], off offset:512
	s_and_saveexec_b64 s[6:7], s[40:41]
	s_cbranch_execz .LBB0_101
	s_waitcnt vmcnt(15)
	v_pk_add_f32 v[30:31], v[86:87], v[144:145]
	v_pk_add_f32 v[28:29], v[84:85], v[142:143]
	s_waitcnt vmcnt(12)
	v_pk_add_f32 v[26:27], v[98:99], v[152:153]
	v_pk_add_f32 v[24:25], v[96:97], v[138:139]
	s_waitcnt vmcnt(9)
	v_pk_add_f32 v[22:23], v[106:107], v[166:167]
	v_pk_add_f32 v[20:21], v[104:105], v[164:165]
	s_waitcnt vmcnt(6)
	v_pk_add_f32 v[18:19], v[110:111], v[168:169]
	v_pk_add_f32 v[16:17], v[108:109], v[154:155]
	v_cmp_lt_i32_e32 vcc, s90, v134
	s_and_saveexec_b64 s[2:3], vcc
	s_cbranch_execz .LBB0_100
	v_add_u32_e32 v156, 0xffff8000, v134
	v_lshlrev_b64 v[36:37], 12, v[156:157]
	v_lshl_add_u64 v[36:37], v[126:127], 0, v[36:37]
	global_store_dwordx4 v[36:37], v[28:31], off
	global_store_dwordx4 v[36:37], v[24:27], off offset:1024
	global_store_dwordx4 v[36:37], v[20:23], off offset:2048
	global_store_dwordx4 v[36:37], v[16:19], off offset:3072
	s_branch .LBB0_100

.Lattn_sm:
	v_pk_add_f32 v[92:93], v[92:93], v[130:131] op_sel_hi:[1,0] neg_lo:[0,1] neg_hi:[0,1]
	v_pk_add_f32 v[94:95], v[94:95], v[130:131] op_sel_hi:[1,0] neg_lo:[0,1] neg_hi:[0,1]
	v_pk_add_f32 v[96:97], v[96:97], v[130:131] op_sel_hi:[1,0] neg_lo:[0,1] neg_hi:[0,1]
	v_pk_add_f32 v[98:99], v[98:99], v[130:131] op_sel_hi:[1,0] neg_lo:[0,1] neg_hi:[0,1]
	v_pk_add_f32 v[100:101], v[100:101], v[130:131] op_sel_hi:[1,0] neg_lo:[0,1] neg_hi:[0,1]
	v_pk_add_f32 v[102:103], v[102:103], v[130:131] op_sel_hi:[1,0] neg_lo:[0,1] neg_hi:[0,1]
	v_pk_add_f32 v[104:105], v[104:105], v[130:131] op_sel_hi:[1,0] neg_lo:[0,1] neg_hi:[0,1]
	v_pk_add_f32 v[106:107], v[106:107], v[130:131] op_sel_hi:[1,0] neg_lo:[0,1] neg_hi:[0,1]
	v_exp_f32_e32 v92, v92
	v_exp_f32_e32 v93, v93
	v_exp_f32_e32 v94, v94
	v_exp_f32_e32 v95, v95
	v_exp_f32_e32 v96, v96
	v_exp_f32_e32 v97, v97
	v_exp_f32_e32 v98, v98
	v_exp_f32_e32 v99, v99
	v_exp_f32_e32 v100, v100
	v_exp_f32_e32 v101, v101
	v_exp_f32_e32 v102, v102
	v_exp_f32_e32 v103, v103
	v_exp_f32_e32 v104, v104
	v_exp_f32_e32 v105, v105
	v_exp_f32_e32 v106, v106
	v_exp_f32_e32 v107, v107
	v_cvt_pk_bf16_f32 v92, v92, v93
	v_cvt_pk_bf16_f32 v93, v94, v95
	v_cvt_pk_bf16_f32 v94, v96, v97
	v_cvt_pk_bf16_f32 v95, v98, v99
	v_cvt_pk_bf16_f32 v96, v100, v101
	v_cvt_pk_bf16_f32 v97, v102, v103
	v_cvt_pk_bf16_f32 v98, v104, v105
	v_cvt_pk_bf16_f32 v99, v106, v107
	v_mov_b32_e32 v100, s52
	v_mov_b32_e32 v101, s52
	v_mov_b32_e32 v102, s52
	v_mov_b32_e32 v103, s52
	v_pk_add_f32 v[76:77], v[76:77], v[128:129] op_sel_hi:[1,0] neg_lo:[0,1] neg_hi:[0,1]
	v_pk_add_f32 v[78:79], v[78:79], v[128:129] op_sel_hi:[1,0] neg_lo:[0,1] neg_hi:[0,1]
	v_pk_add_f32 v[80:81], v[80:81], v[128:129] op_sel_hi:[1,0] neg_lo:[0,1] neg_hi:[0,1]
	v_pk_add_f32 v[82:83], v[82:83], v[128:129] op_sel_hi:[1,0] neg_lo:[0,1] neg_hi:[0,1]
	v_pk_add_f32 v[84:85], v[84:85], v[128:129] op_sel_hi:[1,0] neg_lo:[0,1] neg_hi:[0,1]
	v_pk_add_f32 v[86:87], v[86:87], v[128:129] op_sel_hi:[1,0] neg_lo:[0,1] neg_hi:[0,1]
	v_pk_add_f32 v[88:89], v[88:89], v[128:129] op_sel_hi:[1,0] neg_lo:[0,1] neg_hi:[0,1]
	v_pk_add_f32 v[90:91], v[90:91], v[128:129] op_sel_hi:[1,0] neg_lo:[0,1] neg_hi:[0,1]
	v_exp_f32_e32 v76, v76
	v_exp_f32_e32 v77, v77
	v_exp_f32_e32 v78, v78
	v_exp_f32_e32 v79, v79
	v_exp_f32_e32 v80, v80
	v_exp_f32_e32 v81, v81
	v_exp_f32_e32 v82, v82
	v_exp_f32_e32 v83, v83
	v_exp_f32_e32 v84, v84
	v_exp_f32_e32 v85, v85
	v_exp_f32_e32 v86, v86
	v_exp_f32_e32 v87, v87
	v_exp_f32_e32 v88, v88
	v_exp_f32_e32 v89, v89
	v_exp_f32_e32 v90, v90
	v_exp_f32_e32 v91, v91
	v_cvt_pk_bf16_f32 v76, v76, v77
	v_cvt_pk_bf16_f32 v77, v78, v79
	v_cvt_pk_bf16_f32 v78, v80, v81
	v_cvt_pk_bf16_f32 v79, v82, v83
	v_cvt_pk_bf16_f32 v80, v84, v85
	v_cvt_pk_bf16_f32 v81, v86, v87
	v_cvt_pk_bf16_f32 v82, v88, v89
	v_cvt_pk_bf16_f32 v83, v90, v91
	s_add_i32 s7, s7, 1
	s_bitcmp1_b32 s7, 0
	s_cselect_b32 s2, 0x5800, 0
	s_add_i32 s10, s2, 0
	v_add_u32_e32 v127, s10, v139
	v_add_u32_e32 v129, s10, v140
	v_add_u32_e32 v131, s10, v116
	s_waitcnt vmcnt(2)
	ds_write_b128 v127, v[72:75]
	s_waitcnt vmcnt(0)
	ds_write_b128 v131, v[64:67] offset:13312
	s_and_b64 vcc, exec, s[42:43]
	s_cbranch_vccz .Lattn_skipw
	ds_write_b128 v129, v[68:71]
.Lattn_skipw:
	s_waitcnt lgkmcnt(15)
	v_mfma_f32_16x16x32_bf16 v[60:63], v[234:237], v[92:95], v[60:63]
	v_mfma_f32_16x16x32_bf16 v[56:59], v[234:237], v[76:79], v[56:59]
	s_waitcnt lgkmcnt(14)
	v_mfma_f32_16x16x32_bf16 v[60:63], v[238:241], v[96:99], v[60:63]
	v_mfma_f32_16x16x32_bf16 v[56:59], v[238:241], v[80:83], v[56:59]
	s_waitcnt lgkmcnt(12)
	v_mfma_f32_16x16x32_bf16 v[52:55], v[242:245], v[92:95], v[52:55]
	v_mfma_f32_16x16x32_bf16 v[48:51], v[242:245], v[76:79], v[48:51]
	s_waitcnt lgkmcnt(10)
	v_mfma_f32_16x16x32_bf16 v[52:55], v[246:249], v[96:99], v[52:55]
	v_mfma_f32_16x16x32_bf16 v[48:51], v[246:249], v[80:83], v[48:51]
	s_waitcnt lgkmcnt(8)
	v_mfma_f32_16x16x32_bf16 v[44:47], v[250:253], v[92:95], v[44:47]
	v_mfma_f32_16x16x32_bf16 v[40:43], v[250:253], v[76:79], v[40:43]
	s_waitcnt lgkmcnt(6)
	v_mfma_f32_16x16x32_bf16 v[44:47], v[148:151], v[96:99], v[44:47]
	v_mfma_f32_16x16x32_bf16 v[40:43], v[148:151], v[80:83], v[40:43]
	s_waitcnt lgkmcnt(4)
	v_mfma_f32_16x16x32_bf16 v[36:39], v[152:155], v[92:95], v[36:39]
	v_mfma_f32_16x16x32_bf16 v[32:35], v[152:155], v[76:79], v[32:35]
	s_waitcnt lgkmcnt(2)
	v_mfma_f32_16x16x32_bf16 v[36:39], v[206:209], v[96:99], v[36:39]
	v_mfma_f32_16x16x32_bf16 v[32:35], v[206:209], v[80:83], v[32:35]
	v_mfma_f32_16x16x32_bf16 v[28:31], v[100:103], v[92:95], v[28:31]
	v_mfma_f32_16x16x32_bf16 v[24:27], v[100:103], v[76:79], v[24:27]
	v_mfma_f32_16x16x32_bf16 v[28:31], v[100:103], v[96:99], v[28:31]
	v_mfma_f32_16x16x32_bf16 v[24:27], v[100:103], v[80:83], v[24:27]
	s_waitcnt lgkmcnt(0)
	s_barrier
	v_lshl_add_u64 v[132:133], v[132:133], 0, s[50:51]
	v_lshl_add_u64 v[134:135], v[134:135], 0, s[4:5]
	v_lshl_add_u64 v[136:137], v[136:137], 0, s[4:5]
	s_cmp_eq_u32 s6, s7
	s_cbranch_scc0 .LBB0_175
	s_branch .LBB0_161

.LBB0_300:
	s_or_b64 exec, exec, s[6:7]
	s_waitcnt vmcnt(4)
	v_lshlrev_b32_e32 v96, 16, v88
	s_waitcnt vmcnt(3)
	v_lshlrev_b32_e32 v89, 16, v89
	v_lshlrev_b32_e32 v88, 16, v87
	s_waitcnt vmcnt(1)
	v_lshlrev_b32_e32 v93, 16, v86
	v_lshlrev_b32_e32 v92, 16, v85
	v_pk_mul_f32 v[90:91], v[88:89], v[88:89]
	v_pk_mul_f32 v[94:95], v[92:93], v[92:93]
	v_fma_f32 v87, v96, v96, v90
	v_mov_b32_e32 v86, v94
	v_mov_b32_e32 v90, v95
	v_pk_add_f32 v[86:87], v[86:87], v[90:91]
	s_brev_b32 s2, 60
	s_mov_b32 s3, 0x3baaaaab
	s_waitcnt vmcnt(0)
	v_lshlrev_b32_e32 v84, 16, v84
	s_waitcnt lgkmcnt(0)
	s_nop 1
	v_add_f32_dpp v86, v86, v86 quad_perm:[1,0,3,2] row_mask:0xf bank_mask:0xf
	v_add_f32_dpp v87, v87, v87 quad_perm:[1,0,3,2] row_mask:0xf bank_mask:0xf
	s_waitcnt lgkmcnt(0)
	s_nop 1
	v_add_f32_dpp v86, v86, v86 quad_perm:[2,3,0,1] row_mask:0xf bank_mask:0xf
	v_add_f32_dpp v87, v87, v87 quad_perm:[2,3,0,1] row_mask:0xf bank_mask:0xf
	s_waitcnt lgkmcnt(0)
	s_nop 1
	v_add_f32_dpp v86, v86, v86 row_half_mirror row_mask:0xf bank_mask:0xf
	v_add_f32_dpp v87, v87, v87 row_half_mirror row_mask:0xf bank_mask:0xf
	s_waitcnt lgkmcnt(0)
	s_nop 1
	v_add_f32_dpp v86, v86, v86 row_mirror row_mask:0xf bank_mask:0xf
	v_add_f32_dpp v87, v87, v87 row_mirror row_mask:0xf bank_mask:0xf
	s_waitcnt lgkmcnt(0)
	v_mov_b32_e32 v90, v86
	v_mov_b32_e32 v91, v87
	s_nop 1
	v_permlane16_swap_b32_e32 v86, v90
	v_permlane16_swap_b32_e32 v87, v91
	v_pk_add_f32 v[86:87], v[86:87], v[90:91]
	s_waitcnt lgkmcnt(0)
	v_mov_b32_e32 v90, v86
	v_mov_b32_e32 v91, v87
	s_nop 1
	v_permlane32_swap_b32_e32 v86, v90
	v_permlane32_swap_b32_e32 v87, v91
	v_pk_add_f32 v[86:87], v[86:87], v[90:91]
	s_nop 0
	v_pk_fma_f32 v[86:87], v[86:87], s[2:3], v[158:159] op_sel_hi:[1,1,0]
	s_nop 0
	v_mul_f32_e32 v85, 0x4b800000, v87
	v_cmp_gt_f32_e64 s[48:49], s82, v87
	v_cmp_gt_f32_e64 s[46:47], s82, v86
	s_nop 0
	v_cndmask_b32_e64 v85, v87, v85, s[48:49]
	v_rsq_f32_e32 v85, v85
	s_nop 0
	v_mul_f32_e32 v87, 0x45800000, v85
	v_cndmask_b32_e64 v85, v85, v87, s[48:49]
	v_mul_f32_e32 v87, 0x4b800000, v86
	v_cndmask_b32_e64 v86, v86, v87, s[46:47]
	v_rsq_f32_e32 v86, v86
	s_nop 0
	v_mul_f32_e32 v87, 0x45800000, v86
	v_cndmask_b32_e64 v90, v86, v87, s[46:47]
	v_mul_f32_e32 v86, v85, v88
	v_mul_f32_e32 v86, v50, v86
	v_cvt_pk_bf16_f32 v88, v86, v157
	v_lshl_add_u64 v[86:87], s[26:27], 0, v[14:15]
	global_store_short v[86:87], v88, off offset:-384
	v_mul_f32_e32 v88, v85, v96
	v_mul_f32_e32 v85, v85, v89
	v_mul_f32_e32 v88, v51, v88
	v_mul_f32_e32 v85, v52, v85
	v_cvt_pk_bf16_f32 v88, v88, v157
	global_store_short v[86:87], v88, off offset:-256
	v_cvt_pk_bf16_f32 v85, v85, v157
	global_store_short v[86:87], v85, off offset:-128
	v_mul_f32_e32 v85, v90, v92
	v_mul_f32_e32 v85, v53, v85
	v_cvt_pk_bf16_f32 v85, v85, v157
	global_store_short v[86:87], v85, off
	v_mul_f32_e32 v85, v90, v93
	v_mul_f32_e32 v85, v54, v85
	v_cvt_pk_bf16_f32 v85, v85, v157
	global_store_short v[86:87], v85, off offset:128
	global_store_short v[86:87], v157, off offset:256
	ds_bpermute_b32 v85, v58, v84
	s_and_saveexec_b64 s[2:3], s[44:45]
	s_xor_b64 s[2:3], exec, s[2:3]
	s_cbranch_execnz .LBB0_304
	s_andn2_saveexec_b64 s[2:3], s[2:3]
	s_cbranch_execnz .LBB0_305

.LBB0_440:
	s_or_b64 exec, exec, s[2:3]
	v_mul_f32_e32 v40, v29, v29
	v_mul_f32_e32 v41, v25, v25
	v_fmac_f32_e32 v40, v28, v28
	v_fmac_f32_e32 v41, v24, v24
	v_fmac_f32_e32 v40, v30, v30
	v_fmac_f32_e32 v41, v26, v26
	v_fmac_f32_e32 v40, v31, v31
	v_fmac_f32_e32 v41, v27, v27
	v_add_f32_e32 v40, v40, v41
	v_mul_f32_e32 v41, v21, v21
	v_fmac_f32_e32 v41, v20, v20
	v_fmac_f32_e32 v41, v22, v22
	v_fmac_f32_e32 v41, v23, v23
	v_add_f32_e32 v40, v40, v41
	v_mul_f32_e32 v41, v17, v17
	v_fmac_f32_e32 v41, v16, v16
	v_fmac_f32_e32 v41, v18, v18
	v_fmac_f32_e32 v41, v19, v19
	v_add_f32_e32 v40, v40, v41
	v_ashrrev_i32_e32 v135, 31, v134
	v_pk_add_f32 v[44:45], v[50:51], 1.0 op_sel_hi:[1,0]
	v_pk_add_f32 v[46:47], v[48:49], 1.0 op_sel_hi:[1,0]
	v_lshlrev_b64 v[42:43], 11, v[134:135]
	s_waitcnt lgkmcnt(0)
	s_nop 1
	v_add_f32_dpp v40, v40, v40 quad_perm:[1,0,3,2] row_mask:0xf bank_mask:0xf
	v_pk_add_f32 v[36:37], v[36:37], 1.0 op_sel_hi:[1,0]
	s_waitcnt lgkmcnt(0)
	s_nop 1
	v_add_f32_dpp v40, v40, v40 quad_perm:[2,3,0,1] row_mask:0xf bank_mask:0xf
	s_waitcnt lgkmcnt(0)
	s_nop 1
	v_add_f32_dpp v40, v40, v40 row_half_mirror row_mask:0xf bank_mask:0xf
	s_waitcnt lgkmcnt(0)
	s_nop 1
	v_add_f32_dpp v40, v40, v40 row_mirror row_mask:0xf bank_mask:0xf
	s_waitcnt lgkmcnt(0)
	v_mov_b32_e32 v41, v40
	s_nop 1
	v_permlane16_swap_b32_e32 v40, v41
	v_add_f32_e32 v40, v40, v41
	s_waitcnt lgkmcnt(0)
	v_mov_b32_e32 v41, v40
	s_nop 1
	v_permlane32_swap_b32_e32 v40, v41
	v_add_f32_e32 v40, v40, v41
	v_fmamk_f32 v40, v40, 0x3a800000, v158
	v_cmp_gt_f32_e32 vcc, s82, v40
	v_mul_f32_e32 v41, 0x4b800000, v40
	s_nop 0
	v_cndmask_b32_e32 v40, v40, v41, vcc
	v_rsq_f32_e32 v40, v40
	s_nop 0
	v_mul_f32_e32 v41, 0x45800000, v40
	v_cndmask_b32_e32 v40, v40, v41, vcc
	v_pk_mul_f32 v[30:31], v[30:31], v[40:41] op_sel_hi:[1,0]
	v_pk_mul_f32 v[28:29], v[28:29], v[40:41] op_sel_hi:[1,0]
	v_pk_mul_f32 v[30:31], v[2:3], v[30:31]
	v_pk_mul_f32 v[28:29], v[0:1], v[28:29]
	v_pk_fma_f32 v[30:31], v[44:45], v[30:31], v[54:55]
	v_pk_fma_f32 v[28:29], v[46:47], v[28:29], v[52:53]
	v_pk_mul_f32 v[24:25], v[24:25], v[40:41] op_sel_hi:[1,0]
	v_cvt_pk_bf16_f32 v28, v28, v29
	v_cvt_pk_bf16_f32 v29, v30, v31
	v_lshl_add_u64 v[30:31], v[128:129], 0, v[42:43]
	v_pk_mul_f32 v[26:27], v[26:27], v[40:41] op_sel_hi:[1,0]
	v_pk_mul_f32 v[24:25], v[4:5], v[24:25]
	global_store_dwordx2 v[30:31], v[28:29], off
	v_pk_mul_f32 v[26:27], v[6:7], v[26:27]
	v_pk_add_f32 v[28:29], v[38:39], 1.0 op_sel_hi:[1,0]
	v_pk_fma_f32 v[24:25], v[36:37], v[24:25], v[32:33]
	v_pk_fma_f32 v[26:27], v[28:29], v[26:27], v[34:35]
	v_cvt_pk_bf16_f32 v24, v24, v25
	v_pk_mul_f32 v[22:23], v[22:23], v[40:41] op_sel_hi:[1,0]
	v_cvt_pk_bf16_f32 v25, v26, v27
	v_pk_mul_f32 v[20:21], v[20:21], v[40:41] op_sel_hi:[1,0]
	global_store_dwordx2 v[30:31], v[24:25], off offset:512
	v_pk_mul_f32 v[20:21], v[8:9], v[20:21]
	v_pk_mul_f32 v[22:23], v[10:11], v[22:23]
	v_pk_add_f32 v[24:25], v[62:63], 1.0 op_sel_hi:[1,0]
	v_pk_add_f32 v[26:27], v[60:61], 1.0 op_sel_hi:[1,0]
	v_pk_fma_f32 v[22:23], v[24:25], v[22:23], v[58:59]
	v_pk_fma_f32 v[20:21], v[26:27], v[20:21], v[56:57]
	v_pk_mul_f32 v[16:17], v[16:17], v[40:41] op_sel_hi:[1,0]
	v_cvt_pk_bf16_f32 v20, v20, v21
	v_cvt_pk_bf16_f32 v21, v22, v23
	v_pk_mul_f32 v[18:19], v[18:19], v[40:41] op_sel_hi:[1,0]
	v_pk_mul_f32 v[16:17], v[12:13], v[16:17]
	s_waitcnt vmcnt(7)
	v_pk_add_f32 v[22:23], v[80:81], 1.0 op_sel_hi:[1,0]
	global_store_dwordx2 v[30:31], v[20:21], off offset:1024
	v_pk_mul_f32 v[18:19], v[14:15], v[18:19]
	v_pk_add_f32 v[20:21], v[82:83], 1.0 op_sel_hi:[1,0]
	s_waitcnt vmcnt(7)
	v_pk_fma_f32 v[16:17], v[22:23], v[16:17], v[76:77]
	v_pk_fma_f32 v[18:19], v[20:21], v[18:19], v[78:79]
	v_cvt_pk_bf16_f32 v16, v16, v17
	s_nop 0
	v_cvt_pk_bf16_f32 v17, v18, v19
	global_store_dwordx2 v[30:31], v[16:17], off offset:1536

.LBB0_468:
	s_or_b64 exec, exec, s[2:3]
	v_mul_f32_e32 v92, v117, v117
	v_mul_f32_e32 v93, v113, v113
	v_fmac_f32_e32 v92, v116, v116
	v_fmac_f32_e32 v93, v112, v112
	v_fmac_f32_e32 v92, v118, v118
	v_fmac_f32_e32 v93, v114, v114
	v_fmac_f32_e32 v92, v119, v119
	v_fmac_f32_e32 v93, v115, v115
	v_add_f32_e32 v92, v92, v93
	v_mul_f32_e32 v93, v89, v89
	v_fmac_f32_e32 v93, v88, v88
	v_fmac_f32_e32 v93, v90, v90
	v_fmac_f32_e32 v93, v91, v91
	v_add_f32_e32 v92, v92, v93
	v_mul_f32_e32 v93, v73, v73
	v_fmac_f32_e32 v93, v72, v72
	v_fmac_f32_e32 v93, v74, v74
	v_fmac_f32_e32 v93, v75, v75
	v_add_f32_e32 v92, v92, v93
	v_pk_add_f32 v[20:21], v[20:21], 1.0 op_sel_hi:[1,0]
	v_pk_add_f32 v[22:23], v[22:23], 1.0 op_sel_hi:[1,0]
	s_waitcnt lgkmcnt(0)
	s_nop 1
	v_add_f32_dpp v92, v92, v92 quad_perm:[1,0,3,2] row_mask:0xf bank_mask:0xf
	s_waitcnt lgkmcnt(0)
	s_nop 1
	v_add_f32_dpp v92, v92, v92 quad_perm:[2,3,0,1] row_mask:0xf bank_mask:0xf
	s_waitcnt lgkmcnt(0)
	s_nop 1
	v_add_f32_dpp v92, v92, v92 row_half_mirror row_mask:0xf bank_mask:0xf
	s_waitcnt lgkmcnt(0)
	s_nop 1
	v_add_f32_dpp v92, v92, v92 row_mirror row_mask:0xf bank_mask:0xf
	s_waitcnt lgkmcnt(0)
	v_mov_b32_e32 v93, v92
	s_nop 1
	v_permlane16_swap_b32_e32 v92, v93
	v_add_f32_e32 v92, v92, v93
	s_waitcnt lgkmcnt(0)
	v_mov_b32_e32 v93, v92
	s_nop 1
	v_permlane32_swap_b32_e32 v92, v93
	v_add_f32_e32 v92, v92, v93
	v_fmamk_f32 v92, v92, 0x3a800000, v158
	v_cmp_gt_f32_e32 vcc, s82, v92
	v_mul_f32_e32 v93, 0x4b800000, v92
	s_nop 0
	v_cndmask_b32_e32 v92, v92, v93, vcc
	v_rsq_f32_e32 v92, v92
	s_nop 0
	v_mul_f32_e32 v93, 0x45800000, v92
	v_cndmask_b32_e32 v92, v92, v93, vcc
	v_pk_mul_f32 v[100:101], v[116:117], v[92:93] op_sel_hi:[1,0]
	v_pk_mul_f32 v[94:95], v[118:119], v[92:93] op_sel_hi:[1,0]
	v_pk_mul_f32 v[100:101], v[0:1], v[100:101]
	v_pk_mul_f32 v[94:95], v[2:3], v[94:95]
	v_pk_fma_f32 v[20:21], v[20:21], v[100:101], v[24:25]
	v_pk_fma_f32 v[22:23], v[22:23], v[94:95], v[26:27]
	v_cvt_pk_bf16_f32 v20, v20, v21
	v_pk_add_f32 v[24:25], v[30:31], 1.0 op_sel_hi:[1,0]
	v_cvt_pk_bf16_f32 v21, v22, v23
	global_store_dwordx2 v[132:133], v[20:21], off offset:-1024
	v_pk_mul_f32 v[20:21], v[114:115], v[92:93] op_sel_hi:[1,0]
	v_pk_mul_f32 v[22:23], v[112:113], v[92:93] op_sel_hi:[1,0]
	v_pk_mul_f32 v[20:21], v[6:7], v[20:21]
	v_pk_mul_f32 v[22:23], v[4:5], v[22:23]
	v_pk_add_f32 v[26:27], v[28:29], 1.0 op_sel_hi:[1,0]
	v_pk_fma_f32 v[18:19], v[24:25], v[20:21], v[18:19]
	v_pk_fma_f32 v[16:17], v[26:27], v[22:23], v[16:17]
	v_pk_add_f32 v[22:23], v[44:45], 1.0 op_sel_hi:[1,0]
	v_cvt_pk_bf16_f32 v16, v16, v17
	v_cvt_pk_bf16_f32 v17, v18, v19
	v_pk_mul_f32 v[18:19], v[88:89], v[92:93] op_sel_hi:[1,0]
	global_store_dwordx2 v[132:133], v[16:17], off offset:-512
	v_pk_mul_f32 v[16:17], v[90:91], v[92:93] op_sel_hi:[1,0]
	v_pk_mul_f32 v[18:19], v[8:9], v[18:19]
	v_pk_mul_f32 v[16:17], v[10:11], v[16:17]
	v_pk_add_f32 v[20:21], v[46:47], 1.0 op_sel_hi:[1,0]
	v_pk_fma_f32 v[18:19], v[22:23], v[18:19], v[40:41]
	v_pk_fma_f32 v[16:17], v[20:21], v[16:17], v[42:43]
	v_cvt_pk_bf16_f32 v18, v18, v19
	s_waitcnt vmcnt(15)
	v_pk_add_f32 v[22:23], v[68:69], 1.0 op_sel_hi:[1,0]
	v_cvt_pk_bf16_f32 v19, v16, v17
	global_store_dwordx2 v[132:133], v[18:19], off
	v_pk_mul_f32 v[18:19], v[72:73], v[92:93] op_sel_hi:[1,0]
	v_pk_mul_f32 v[16:17], v[74:75], v[92:93] op_sel_hi:[1,0]
	v_pk_mul_f32 v[18:19], v[12:13], v[18:19]
	v_pk_mul_f32 v[16:17], v[14:15], v[16:17]
	v_pk_add_f32 v[20:21], v[70:71], 1.0 op_sel_hi:[1,0]
	s_waitcnt vmcnt(15)
	v_pk_fma_f32 v[18:19], v[22:23], v[18:19], v[64:65]
	v_pk_fma_f32 v[16:17], v[20:21], v[16:17], v[66:67]
	v_cvt_pk_bf16_f32 v18, v18, v19
	s_nop 0
	v_cvt_pk_bf16_f32 v19, v16, v17
	global_store_dwordx2 v[132:133], v[18:19], off offset:512
	s_and_saveexec_b64 s[6:7], s[40:41]
	s_cbranch_execz .LBB0_441
	s_waitcnt vmcnt(15)
	v_pk_add_f32 v[30:31], v[86:87], v[144:145]
	v_pk_add_f32 v[28:29], v[84:85], v[142:143]
	s_waitcnt vmcnt(12)
	v_pk_add_f32 v[26:27], v[98:99], v[152:153]
	v_pk_add_f32 v[24:25], v[96:97], v[138:139]
	s_waitcnt vmcnt(9)
	v_pk_add_f32 v[22:23], v[106:107], v[166:167]
	v_pk_add_f32 v[20:21], v[104:105], v[164:165]
	s_waitcnt vmcnt(6)
	v_pk_add_f32 v[18:19], v[110:111], v[168:169]
	v_pk_add_f32 v[16:17], v[108:109], v[154:155]
	v_cmp_lt_i32_e32 vcc, s90, v134
	s_and_saveexec_b64 s[2:3], vcc
	s_cbranch_execz .LBB0_440
	v_add_u32_e32 v156, 0xffff8000, v134
	v_lshlrev_b64 v[40:41], 12, v[156:157]
	v_lshl_add_u64 v[40:41], v[126:127], 0, v[40:41]
	global_store_dwordx4 v[40:41], v[28:31], off
	global_store_dwordx4 v[40:41], v[24:27], off offset:1024
	global_store_dwordx4 v[40:41], v[20:23], off offset:2048
	global_store_dwordx4 v[40:41], v[16:19], off offset:3072
	s_branch .LBB0_440

.LBB0_566:
	s_or_b64 exec, exec, s[2:3]
	v_mul_f32_e32 v56, v53, v53
	v_mul_f32_e32 v57, v33, v33
	v_fmac_f32_e32 v56, v52, v52
	v_fmac_f32_e32 v57, v32, v32
	v_fmac_f32_e32 v56, v54, v54
	v_fmac_f32_e32 v57, v34, v34
	v_fmac_f32_e32 v56, v55, v55
	v_fmac_f32_e32 v57, v35, v35
	v_add_f32_e32 v56, v56, v57
	v_mul_f32_e32 v57, v29, v29
	v_fmac_f32_e32 v57, v28, v28
	v_fmac_f32_e32 v57, v30, v30
	v_fmac_f32_e32 v57, v31, v31
	v_add_f32_e32 v56, v56, v57
	v_mul_f32_e32 v57, v25, v25
	v_fmac_f32_e32 v57, v24, v24
	v_fmac_f32_e32 v57, v26, v26
	v_fmac_f32_e32 v57, v27, v27
	v_add_f32_e32 v56, v56, v57
	v_ashrrev_i32_e32 v135, 31, v134
	v_pk_add_f32 v[50:51], v[50:51], 1.0 op_sel_hi:[1,0]
	v_pk_add_f32 v[48:49], v[48:49], 1.0 op_sel_hi:[1,0]
	v_lshlrev_b64 v[58:59], 11, v[134:135]
	s_waitcnt lgkmcnt(0)
	s_nop 1
	v_add_f32_dpp v56, v56, v56 quad_perm:[1,0,3,2] row_mask:0xf bank_mask:0xf
	v_pk_add_f32 v[22:23], v[22:23], 1.0 op_sel_hi:[1,0]
	v_pk_add_f32 v[20:21], v[20:21], 1.0 op_sel_hi:[1,0]
	s_waitcnt lgkmcnt(0)
	s_nop 1
	v_add_f32_dpp v56, v56, v56 quad_perm:[2,3,0,1] row_mask:0xf bank_mask:0xf
	s_waitcnt lgkmcnt(0)
	s_nop 1
	v_add_f32_dpp v56, v56, v56 row_half_mirror row_mask:0xf bank_mask:0xf
	s_waitcnt lgkmcnt(0)
	s_nop 1
	v_add_f32_dpp v56, v56, v56 row_mirror row_mask:0xf bank_mask:0xf
	s_waitcnt lgkmcnt(0)
	v_mov_b32_e32 v57, v56
	s_nop 1
	v_permlane16_swap_b32_e32 v56, v57
	v_add_f32_e32 v56, v56, v57
	s_waitcnt lgkmcnt(0)
	v_mov_b32_e32 v57, v56
	s_nop 1
	v_permlane32_swap_b32_e32 v56, v57
	v_add_f32_e32 v56, v56, v57
	v_fmamk_f32 v56, v56, 0x3a800000, v158
	v_cmp_gt_f32_e32 vcc, s82, v56
	v_mul_f32_e32 v57, 0x4b800000, v56
	s_nop 0
	v_cndmask_b32_e32 v56, v56, v57, vcc
	v_rsq_f32_e32 v56, v56
	s_nop 0
	v_mul_f32_e32 v57, 0x45800000, v56
	v_cndmask_b32_e32 v56, v56, v57, vcc
	v_pk_mul_f32 v[54:55], v[54:55], v[56:57] op_sel_hi:[1,0]
	v_pk_mul_f32 v[52:53], v[52:53], v[56:57] op_sel_hi:[1,0]
	v_pk_mul_f32 v[54:55], v[2:3], v[54:55]
	v_pk_mul_f32 v[52:53], v[0:1], v[52:53]
	v_pk_mul_f32 v[34:35], v[34:35], v[56:57] op_sel_hi:[1,0]
	v_pk_mul_f32 v[32:33], v[32:33], v[56:57] op_sel_hi:[1,0]
	v_pk_fma_f32 v[42:43], v[50:51], v[54:55], v[42:43]
	v_pk_fma_f32 v[40:41], v[48:49], v[52:53], v[40:41]
	v_pk_mul_f32 v[32:33], v[4:5], v[32:33]
	v_pk_mul_f32 v[34:35], v[6:7], v[34:35]
	v_cvt_pk_bf16_f32 v40, v40, v41
	v_cvt_pk_bf16_f32 v41, v42, v43
	v_lshl_add_u64 v[42:43], v[128:129], 0, v[58:59]
	v_pk_fma_f32 v[18:19], v[22:23], v[34:35], v[18:19]
	v_pk_fma_f32 v[16:17], v[20:21], v[32:33], v[16:17]
	global_store_dwordx2 v[42:43], v[40:41], off
	v_cvt_pk_bf16_f32 v16, v16, v17
	v_cvt_pk_bf16_f32 v17, v18, v19
	v_pk_mul_f32 v[18:19], v[28:29], v[56:57] op_sel_hi:[1,0]
	global_store_dwordx2 v[42:43], v[16:17], off offset:512
	v_pk_mul_f32 v[16:17], v[30:31], v[56:57] op_sel_hi:[1,0]
	v_pk_mul_f32 v[18:19], v[8:9], v[18:19]
	v_pk_add_f32 v[22:23], v[44:45], 1.0 op_sel_hi:[1,0]
	v_pk_mul_f32 v[16:17], v[10:11], v[16:17]
	v_pk_add_f32 v[20:21], v[46:47], 1.0 op_sel_hi:[1,0]
	v_pk_fma_f32 v[18:19], v[22:23], v[18:19], v[36:37]
	v_pk_fma_f32 v[16:17], v[20:21], v[16:17], v[38:39]
	v_cvt_pk_bf16_f32 v18, v18, v19
	s_waitcnt vmcnt(7)
	v_pk_add_f32 v[22:23], v[76:77], 1.0 op_sel_hi:[1,0]
	v_cvt_pk_bf16_f32 v19, v16, v17
	global_store_dwordx2 v[42:43], v[18:19], off offset:1024
	v_pk_mul_f32 v[18:19], v[24:25], v[56:57] op_sel_hi:[1,0]
	v_pk_mul_f32 v[16:17], v[26:27], v[56:57] op_sel_hi:[1,0]
	v_pk_mul_f32 v[18:19], v[12:13], v[18:19]
	v_pk_mul_f32 v[16:17], v[14:15], v[16:17]
	v_pk_add_f32 v[20:21], v[78:79], 1.0 op_sel_hi:[1,0]
	s_waitcnt vmcnt(7)
	v_pk_fma_f32 v[18:19], v[22:23], v[18:19], v[72:73]
	v_pk_fma_f32 v[16:17], v[20:21], v[16:17], v[74:75]
	v_cvt_pk_bf16_f32 v18, v18, v19
	s_nop 0
	v_cvt_pk_bf16_f32 v19, v16, v17
	global_store_dwordx2 v[42:43], v[18:19], off offset:1536

.LBB0_594:
	s_or_b64 exec, exec, s[2:3]
	v_mul_f32_e32 v96, v117, v117
	v_mul_f32_e32 v97, v113, v113
	v_fmac_f32_e32 v96, v116, v116
	v_fmac_f32_e32 v97, v112, v112
	v_fmac_f32_e32 v96, v118, v118
	v_fmac_f32_e32 v97, v114, v114
	v_fmac_f32_e32 v96, v119, v119
	v_fmac_f32_e32 v97, v115, v115
	v_add_f32_e32 v96, v96, v97
	v_mul_f32_e32 v97, v93, v93
	v_fmac_f32_e32 v97, v92, v92
	v_fmac_f32_e32 v97, v94, v94
	v_fmac_f32_e32 v97, v95, v95
	v_add_f32_e32 v96, v96, v97
	v_mul_f32_e32 v97, v85, v85
	v_fmac_f32_e32 v97, v84, v84
	v_fmac_f32_e32 v97, v86, v86
	v_fmac_f32_e32 v97, v87, v87
	v_add_f32_e32 v96, v96, v97
	v_pk_add_f32 v[32:33], v[32:33], 1.0 op_sel_hi:[1,0]
	v_pk_add_f32 v[34:35], v[34:35], 1.0 op_sel_hi:[1,0]
	s_waitcnt lgkmcnt(0)
	s_nop 1
	v_add_f32_dpp v96, v96, v96 quad_perm:[1,0,3,2] row_mask:0xf bank_mask:0xf
	s_waitcnt lgkmcnt(0)
	s_nop 1
	v_add_f32_dpp v96, v96, v96 quad_perm:[2,3,0,1] row_mask:0xf bank_mask:0xf
	s_waitcnt lgkmcnt(0)
	s_nop 1
	v_add_f32_dpp v96, v96, v96 row_half_mirror row_mask:0xf bank_mask:0xf
	s_waitcnt lgkmcnt(0)
	s_nop 1
	v_add_f32_dpp v96, v96, v96 row_mirror row_mask:0xf bank_mask:0xf
	s_waitcnt lgkmcnt(0)
	v_mov_b32_e32 v97, v96
	s_nop 1
	v_permlane16_swap_b32_e32 v96, v97
	v_add_f32_e32 v96, v96, v97
	s_waitcnt lgkmcnt(0)
	v_mov_b32_e32 v97, v96
	s_nop 1
	v_permlane32_swap_b32_e32 v96, v97
	v_add_f32_e32 v96, v96, v97
	v_fmamk_f32 v96, v96, 0x3a800000, v158
	v_cmp_gt_f32_e32 vcc, s82, v96
	v_mul_f32_e32 v97, 0x4b800000, v96
	s_nop 0
	v_cndmask_b32_e32 v96, v96, v97, vcc
	v_rsq_f32_e32 v96, v96
	s_nop 0
	v_mul_f32_e32 v97, 0x45800000, v96
	v_cndmask_b32_e32 v96, v96, v97, vcc
	v_pk_mul_f32 v[104:105], v[116:117], v[96:97] op_sel_hi:[1,0]
	v_pk_mul_f32 v[98:99], v[118:119], v[96:97] op_sel_hi:[1,0]
	v_pk_mul_f32 v[104:105], v[0:1], v[104:105]
	v_pk_mul_f32 v[98:99], v[2:3], v[98:99]
	v_pk_fma_f32 v[28:29], v[32:33], v[104:105], v[28:29]
	v_pk_fma_f32 v[30:31], v[34:35], v[98:99], v[30:31]
	v_cvt_pk_bf16_f32 v28, v28, v29
	v_pk_add_f32 v[32:33], v[62:63], 1.0 op_sel_hi:[1,0]
	v_cvt_pk_bf16_f32 v29, v30, v31
	global_store_dwordx2 v[132:133], v[28:29], off offset:-1024
	v_pk_mul_f32 v[28:29], v[114:115], v[96:97] op_sel_hi:[1,0]
	v_pk_mul_f32 v[30:31], v[112:113], v[96:97] op_sel_hi:[1,0]
	v_pk_mul_f32 v[28:29], v[6:7], v[28:29]
	v_pk_mul_f32 v[30:31], v[4:5], v[30:31]
	v_pk_add_f32 v[34:35], v[60:61], 1.0 op_sel_hi:[1,0]
	v_pk_fma_f32 v[26:27], v[32:33], v[28:29], v[26:27]
	v_pk_fma_f32 v[24:25], v[34:35], v[30:31], v[24:25]
	v_pk_add_f32 v[30:31], v[56:57], 1.0 op_sel_hi:[1,0]
	v_cvt_pk_bf16_f32 v24, v24, v25
	v_cvt_pk_bf16_f32 v25, v26, v27
	v_pk_mul_f32 v[26:27], v[92:93], v[96:97] op_sel_hi:[1,0]
	global_store_dwordx2 v[132:133], v[24:25], off offset:-512
	v_pk_mul_f32 v[24:25], v[94:95], v[96:97] op_sel_hi:[1,0]
	v_pk_mul_f32 v[26:27], v[8:9], v[26:27]
	v_pk_mul_f32 v[24:25], v[10:11], v[24:25]
	v_pk_add_f32 v[28:29], v[58:59], 1.0 op_sel_hi:[1,0]
	v_pk_fma_f32 v[26:27], v[30:31], v[26:27], v[52:53]
	v_pk_fma_f32 v[24:25], v[28:29], v[24:25], v[54:55]
	v_cvt_pk_bf16_f32 v26, v26, v27
	s_waitcnt vmcnt(15)
	v_pk_add_f32 v[30:31], v[68:69], 1.0 op_sel_hi:[1,0]
	v_cvt_pk_bf16_f32 v27, v24, v25
	global_store_dwordx2 v[132:133], v[26:27], off
	v_pk_mul_f32 v[26:27], v[84:85], v[96:97] op_sel_hi:[1,0]
	v_pk_mul_f32 v[24:25], v[86:87], v[96:97] op_sel_hi:[1,0]
	v_pk_mul_f32 v[26:27], v[12:13], v[26:27]
	v_pk_mul_f32 v[24:25], v[14:15], v[24:25]
	v_pk_add_f32 v[28:29], v[70:71], 1.0 op_sel_hi:[1,0]
	s_waitcnt vmcnt(15)
	v_pk_fma_f32 v[26:27], v[30:31], v[26:27], v[64:65]
	v_pk_fma_f32 v[24:25], v[28:29], v[24:25], v[66:67]
	v_cvt_pk_bf16_f32 v26, v26, v27
	s_nop 0
	v_cvt_pk_bf16_f32 v27, v24, v25
	global_store_dwordx2 v[132:133], v[26:27], off offset:512
	s_and_saveexec_b64 s[6:7], s[38:39]
	s_cbranch_execz .LBB0_567
	s_waitcnt vmcnt(15)
	v_pk_add_f32 v[54:55], v[82:83], v[140:141]
	v_pk_add_f32 v[52:53], v[80:81], v[138:139]
	s_waitcnt vmcnt(12)
	v_pk_add_f32 v[34:35], v[90:91], v[146:147]
	v_pk_add_f32 v[32:33], v[88:89], v[142:143]
	s_waitcnt vmcnt(9)
	v_pk_add_f32 v[30:31], v[102:103], v[164:165]
	v_pk_add_f32 v[28:29], v[100:101], v[162:163]
	s_waitcnt vmcnt(6)
	v_pk_add_f32 v[26:27], v[110:111], v[168:169]
	v_pk_add_f32 v[24:25], v[108:109], v[154:155]
	v_cmp_lt_i32_e32 vcc, s90, v134
	s_and_saveexec_b64 s[2:3], vcc
	s_cbranch_execz .LBB0_566
	v_add_u32_e32 v156, 0xffff8000, v134
	v_lshlrev_b64 v[56:57], 12, v[156:157]
	v_lshl_add_u64 v[56:57], v[126:127], 0, v[56:57]
	global_store_dwordx4 v[56:57], v[52:55], off
	global_store_dwordx4 v[56:57], v[32:35], off offset:1024
	global_store_dwordx4 v[56:57], v[28:31], off offset:2048
	global_store_dwordx4 v[56:57], v[24:27], off offset:3072
	s_branch .LBB0_566
